# fast attention units: end-of-unit vmcnt(0) store drain removed (waits moved to first consumer across the unit boundary)
# speedup vs baseline: 1.0166x; 1.0069x over previous
; __device__ __forceinline__ unsigned cvt_pk_bf16(float lo, float hi) { unsigned r; asm volatile("v_cvt_pk_bf16_f32 %0, %1, %2" : "=v"(r) : "v"(lo), "v"(hi)); return r; }
; __device__ __forceinline__ int crow(int r, int hi) { return (r & 3) + 8 * (r >> 2) + 4 * hi; }
;     ...
;         if (hib == 0) li2[r32b] = l_reg; asm volatile("s_waitcnt lgkmcnt(0)" ::: "memory");
;         __syncthreads();
;         bf16_t* stash = (bf16_t*)(lds + OFF_Q) + wid2 * 4096;
;         bf16_t* stg = (mode == 1) ? stash : ((bf16_t*)lds + wid2 * 4096);
; #pragma unroll
;         for (int r = 0; r < 16; ++r) { const int orow = crow(r, hib); const float rl = __builtin_amdgcn_rcpf(li2[orow]);
; #pragma unroll
;             for (int d0 = 0; d0 < 4; ++d0) { const float v = o[d0][r] * rl; stg[orow * 128 + d0 * 32 + r32b] = (bf16_t)(cvt_pk_bf16(v, v) & 0xffffu); } }
.LBB0_525:
	s_or_b64 exec, exec, s[0:1]
	v_lshrrev_b32_e32 v66, 3, v64
	v_and_b32_e32 v66, 4, v66
	v_lshl_add_u32 v68, v66, 2, v68
	s_waitcnt lgkmcnt(0)
	s_waitcnt lgkmcnt(0)
	s_barrier
	ds_read_b32 v69, v68
	v_ashrrev_i32_e32 v70, 6, v64
	v_lshl_add_u32 v71, v70, 13, 0
	v_lshlrev_b32_e32 v67, 1, v67
	v_lshlrev_b32_e32 v66, 8, v66
	s_waitcnt lgkmcnt(0)
	v_rcp_f32_e32 v69, v69
	v_add3_u32 v66, v71, v67, v66
	s_add_i32 s51, s51, s15
	s_cmpk_gt_i32 s51, 0x3ff
	v_mul_f32_e32 v0, v0, v69
	v_cvt_pk_bf16_f32 v0, v0, v0
	ds_write_b16 v66, v0
	v_mul_f32_e32 v0, v16, v69
	v_cvt_pk_bf16_f32 v0, v0, v0
	ds_write_b16 v66, v0 offset:64
	v_mul_f32_e32 v0, v32, v69
	v_cvt_pk_bf16_f32 v0, v0, v0
	ds_write_b16 v66, v0 offset:128
	v_mul_f32_e32 v0, v48, v69
	v_cvt_pk_bf16_f32 v0, v0, v0
	ds_read_b32 v16, v68 offset:4
	ds_write_b16 v66, v0 offset:192
	s_waitcnt lgkmcnt(1)
	v_rcp_f32_e32 v16, v16
	s_nop 0
	v_mul_f32_e32 v0, v1, v16
	v_cvt_pk_bf16_f32 v0, v0, v0
	ds_write_b16 v66, v0 offset:256
	v_mul_f32_e32 v0, v17, v16
	v_cvt_pk_bf16_f32 v0, v0, v0
	ds_write_b16 v66, v0 offset:320
	v_mul_f32_e32 v0, v33, v16
	v_cvt_pk_bf16_f32 v0, v0, v0
	ds_write_b16 v66, v0 offset:384
	v_mul_f32_e32 v0, v49, v16
	v_cvt_pk_bf16_f32 v0, v0, v0
	ds_read_b32 v1, v68 offset:8
	ds_write_b16 v66, v0 offset:448
	s_waitcnt lgkmcnt(1)
	v_rcp_f32_e32 v1, v1
	s_nop 0
	v_mul_f32_e32 v0, v2, v1
	v_cvt_pk_bf16_f32 v0, v0, v0
	ds_write_b16 v66, v0 offset:512
	v_mul_f32_e32 v0, v18, v1
	v_cvt_pk_bf16_f32 v0, v0, v0
	ds_write_b16 v66, v0 offset:576
	v_mul_f32_e32 v0, v34, v1
	v_cvt_pk_bf16_f32 v0, v0, v0
	ds_write_b16 v66, v0 offset:640
	v_mul_f32_e32 v0, v50, v1
	v_cvt_pk_bf16_f32 v0, v0, v0
	ds_read_b32 v1, v68 offset:12
	ds_write_b16 v66, v0 offset:704
	v_lshlrev_b32_e32 v2, 5, v70
	s_waitcnt lgkmcnt(1)
	v_rcp_f32_e32 v1, v1
	s_nop 0
	v_mul_f32_e32 v0, v3, v1
	v_cvt_pk_bf16_f32 v0, v0, v0
	ds_write_b16 v66, v0 offset:768
	v_mul_f32_e32 v0, v19, v1
	v_cvt_pk_bf16_f32 v0, v0, v0
	ds_write_b16 v66, v0 offset:832
	v_mul_f32_e32 v0, v35, v1
	v_cvt_pk_bf16_f32 v0, v0, v0
	ds_write_b16 v66, v0 offset:896
	v_mul_f32_e32 v0, v51, v1
	v_cvt_pk_bf16_f32 v0, v0, v0
	ds_read_b32 v1, v68 offset:32
	ds_write_b16 v66, v0 offset:960
	s_waitcnt lgkmcnt(1)
	v_rcp_f32_e32 v1, v1
	s_nop 0
	v_mul_f32_e32 v0, v4, v1
	v_cvt_pk_bf16_f32 v0, v0, v0
	ds_write_b16 v66, v0 offset:2048
	v_mul_f32_e32 v0, v20, v1
	v_cvt_pk_bf16_f32 v0, v0, v0
	ds_write_b16 v66, v0 offset:2112
	v_mul_f32_e32 v0, v36, v1
	v_cvt_pk_bf16_f32 v0, v0, v0
	ds_write_b16 v66, v0 offset:2176
	v_mul_f32_e32 v0, v52, v1
	v_cvt_pk_bf16_f32 v0, v0, v0
	ds_read_b32 v1, v68 offset:36
	ds_write_b16 v66, v0 offset:2240
	v_lshrrev_b32_e32 v4, 4, v65
	s_waitcnt lgkmcnt(1)
	v_rcp_f32_e32 v1, v1
	s_nop 0
	v_mul_f32_e32 v0, v5, v1
	v_cvt_pk_bf16_f32 v0, v0, v0
	ds_write_b16 v66, v0 offset:2304
	v_mul_f32_e32 v0, v21, v1
	v_cvt_pk_bf16_f32 v0, v0, v0
	ds_write_b16 v66, v0 offset:2368
	v_mul_f32_e32 v0, v37, v1
	v_cvt_pk_bf16_f32 v0, v0, v0
	ds_write_b16 v66, v0 offset:2432
	v_mul_f32_e32 v0, v53, v1
	v_cvt_pk_bf16_f32 v0, v0, v0
	ds_read_b32 v1, v68 offset:40
	ds_write_b16 v66, v0 offset:2496
	s_waitcnt lgkmcnt(1)
	v_rcp_f32_e32 v1, v1
	s_nop 0
	v_mul_f32_e32 v0, v6, v1
	v_cvt_pk_bf16_f32 v0, v0, v0
	ds_write_b16 v66, v0 offset:2560
	v_mul_f32_e32 v0, v22, v1
	v_cvt_pk_bf16_f32 v0, v0, v0
	ds_write_b16 v66, v0 offset:2624
	v_mul_f32_e32 v0, v38, v1
	v_cvt_pk_bf16_f32 v0, v0, v0
	ds_write_b16 v66, v0 offset:2688
	v_mul_f32_e32 v0, v54, v1
	v_cvt_pk_bf16_f32 v0, v0, v0
	ds_read_b32 v1, v68 offset:44
	ds_write_b16 v66, v0 offset:2752
	s_waitcnt lgkmcnt(1)
	v_rcp_f32_e32 v1, v1
	s_nop 0
	v_mul_f32_e32 v0, v7, v1
	v_cvt_pk_bf16_f32 v0, v0, v0
	ds_write_b16 v66, v0 offset:2816
	v_mul_f32_e32 v0, v23, v1
	v_cvt_pk_bf16_f32 v0, v0, v0
	ds_write_b16 v66, v0 offset:2880
	v_mul_f32_e32 v0, v39, v1
	v_cvt_pk_bf16_f32 v0, v0, v0
	ds_write_b16 v66, v0 offset:2944
	v_mul_f32_e32 v0, v55, v1
	v_cvt_pk_bf16_f32 v0, v0, v0
	ds_read_b32 v1, v68 offset:64
	ds_write_b16 v66, v0 offset:3008
	s_waitcnt lgkmcnt(1)
	v_rcp_f32_e32 v1, v1
	s_nop 0
	v_mul_f32_e32 v0, v8, v1
	v_cvt_pk_bf16_f32 v0, v0, v0
	ds_write_b16 v66, v0 offset:4096
	v_mul_f32_e32 v0, v24, v1
	v_cvt_pk_bf16_f32 v0, v0, v0
	ds_write_b16 v66, v0 offset:4160
	v_mul_f32_e32 v0, v40, v1
	v_cvt_pk_bf16_f32 v0, v0, v0
	ds_write_b16 v66, v0 offset:4224
	v_mul_f32_e32 v0, v56, v1
	v_cvt_pk_bf16_f32 v0, v0, v0
	ds_read_b32 v1, v68 offset:68
	ds_write_b16 v66, v0 offset:4288
	s_waitcnt lgkmcnt(1)
	v_rcp_f32_e32 v1, v1
	s_nop 0
	v_mul_f32_e32 v0, v9, v1
	v_cvt_pk_bf16_f32 v0, v0, v0
	ds_write_b16 v66, v0 offset:4352
	v_mul_f32_e32 v0, v25, v1
	v_cvt_pk_bf16_f32 v0, v0, v0
	ds_write_b16 v66, v0 offset:4416
	v_mul_f32_e32 v0, v41, v1
	v_cvt_pk_bf16_f32 v0, v0, v0
	ds_write_b16 v66, v0 offset:4480
	v_mul_f32_e32 v0, v57, v1
	v_cvt_pk_bf16_f32 v0, v0, v0
	ds_read_b32 v1, v68 offset:72
	ds_write_b16 v66, v0 offset:4544
	s_waitcnt lgkmcnt(1)
; __device__ __forceinline__ unsigned cvt_pk_bf16(float lo, float hi) { unsigned r; asm volatile("v_cvt_pk_bf16_f32 %0, %1, %2" : "=v"(r) : "v"(lo), "v"(hi)); return r; }
; __device__ __forceinline__ int crow(int r, int hi) { return (r & 3) + 8 * (r >> 2) + 4 * hi; }
;     ...
;         for (int r = 0; r < 16; ++r) { const int orow = crow(r, hib); const float rl = __builtin_amdgcn_rcpf(li2[orow]);
; #pragma unroll
;             for (int d0 = 0; d0 < 4; ++d0) { const float v = o[d0][r] * rl; stg[orow * 128 + d0 * 32 + r32b] = (bf16_t)(cvt_pk_bf16(v, v) & 0xffffu); } }
;         asm volatile("s_waitcnt lgkmcnt(0)" ::: "memory");
;         if (mode != 1) {
;             bf16_t* Ow = Ob + (size_t)(wid2 * QBLK) * LDO;
;             const int ch = lane2 & 15;
;             float gg[8];
;             if (mode == 2) {
; #pragma unroll
;                 for (int e = 0; e < 8; ++e) gg[e] = sg[ch * 8 + e] * 0.8f; }
; #pragma unroll
;             for (int i = 0; i < 8; ++i) { const int row = i * 4 + (lane2 >> 4); u32x4 v = *(const u32x4*)(stg + row * 128 + ch * 8);
;                 if (mode == 2) { const u32x4 v0 = *(const u32x4*)(stash + row * 128 + ch * 8); float x0[8], x1[8]; unpack8(v0, x0); unpack8(v, x1); float ss = 0.f;
; #pragma unroll
;                     for (int e = 0; e < 8; ++e) { x0[e] = x0[e] - lam * x1[e]; ss += x0[e] * x0[e]; }
;                     ss += __shfl_xor(ss, 1); ss += __shfl_xor(ss, 2); ss += __shfl_xor(ss, 4); ss += __shfl_xor(ss, 8);
;                     const float rstd = rsqrtf(ss * (1.0f / 128) + EPS);
; #pragma unroll
;                     for (int e = 0; e < 8; ++e) x0[e] = x0[e] * rstd * gg[e];
;                     v = pack8(x0); }
;                 *(u32x4*)(Ow + (size_t)row * LDO + ch * 8) = v; }
;         }
;     }
;     asm volatile("s_waitcnt vmcnt(0)" ::: "memory");
;     __syncthreads();
	v_rcp_f32_e32 v1, v1
	s_nop 0
	v_mul_f32_e32 v0, v10, v1
	v_cvt_pk_bf16_f32 v0, v0, v0
	ds_write_b16 v66, v0 offset:4608
	v_mul_f32_e32 v0, v26, v1
	v_cvt_pk_bf16_f32 v0, v0, v0
	ds_write_b16 v66, v0 offset:4672
	v_mul_f32_e32 v0, v42, v1
	v_cvt_pk_bf16_f32 v0, v0, v0
	ds_write_b16 v66, v0 offset:4736
	v_mul_f32_e32 v0, v58, v1
	v_cvt_pk_bf16_f32 v0, v0, v0
	ds_read_b32 v1, v68 offset:76
	ds_write_b16 v66, v0 offset:4800
	s_waitcnt lgkmcnt(1)
	v_rcp_f32_e32 v1, v1
	s_nop 0
	v_mul_f32_e32 v0, v11, v1
	v_cvt_pk_bf16_f32 v0, v0, v0
	ds_write_b16 v66, v0 offset:4864
	v_mul_f32_e32 v0, v27, v1
	v_cvt_pk_bf16_f32 v0, v0, v0
	ds_write_b16 v66, v0 offset:4928
	v_mul_f32_e32 v0, v43, v1
	v_cvt_pk_bf16_f32 v0, v0, v0
	ds_write_b16 v66, v0 offset:4992
	v_mul_f32_e32 v0, v59, v1
	v_cvt_pk_bf16_f32 v0, v0, v0
	ds_read_b32 v1, v68 offset:96
	ds_write_b16 v66, v0 offset:5056
	s_waitcnt lgkmcnt(1)
	v_rcp_f32_e32 v1, v1
	s_nop 0
	v_mul_f32_e32 v0, v12, v1
	v_cvt_pk_bf16_f32 v0, v0, v0
	ds_write_b16 v66, v0 offset:6144
	v_mul_f32_e32 v0, v28, v1
	v_cvt_pk_bf16_f32 v0, v0, v0
	ds_write_b16 v66, v0 offset:6208
	v_mul_f32_e32 v0, v44, v1
	v_cvt_pk_bf16_f32 v0, v0, v0
	ds_write_b16 v66, v0 offset:6272
	v_mul_f32_e32 v0, v60, v1
	v_cvt_pk_bf16_f32 v0, v0, v0
	ds_read_b32 v1, v68 offset:100
	ds_write_b16 v66, v0 offset:6336
	s_waitcnt lgkmcnt(1)
	v_rcp_f32_e32 v1, v1
	s_nop 0
	v_mul_f32_e32 v0, v13, v1
	v_cvt_pk_bf16_f32 v0, v0, v0
	ds_write_b16 v66, v0 offset:6400
	v_mul_f32_e32 v0, v29, v1
	v_cvt_pk_bf16_f32 v0, v0, v0
	ds_write_b16 v66, v0 offset:6464
	v_mul_f32_e32 v0, v45, v1
	v_cvt_pk_bf16_f32 v0, v0, v0
	ds_write_b16 v66, v0 offset:6528
	v_mul_f32_e32 v0, v61, v1
	v_cvt_pk_bf16_f32 v0, v0, v0
	ds_read_b32 v1, v68 offset:104
	ds_write_b16 v66, v0 offset:6592
	s_waitcnt lgkmcnt(1)
	v_rcp_f32_e32 v1, v1
	s_nop 0
	v_mul_f32_e32 v0, v14, v1
	v_cvt_pk_bf16_f32 v0, v0, v0
	ds_write_b16 v66, v0 offset:6656
	v_mul_f32_e32 v0, v30, v1
	v_cvt_pk_bf16_f32 v0, v0, v0
	ds_write_b16 v66, v0 offset:6720
	v_mul_f32_e32 v0, v46, v1
	v_cvt_pk_bf16_f32 v0, v0, v0
	ds_write_b16 v66, v0 offset:6784
	v_mul_f32_e32 v0, v62, v1
	v_cvt_pk_bf16_f32 v0, v0, v0
	ds_read_b32 v1, v68 offset:108
	ds_write_b16 v66, v0 offset:6848
	s_waitcnt lgkmcnt(1)
	v_rcp_f32_e32 v1, v1
	s_nop 0
	v_mul_f32_e32 v0, v15, v1
	v_cvt_pk_bf16_f32 v0, v0, v0
	ds_write_b16 v66, v0 offset:6912
	v_mul_f32_e32 v0, v31, v1
	v_cvt_pk_bf16_f32 v0, v0, v0
	ds_write_b16 v66, v0 offset:6976
	v_mul_f32_e32 v0, v47, v1
	v_cvt_pk_bf16_f32 v0, v0, v0
	ds_write_b16 v66, v0 offset:7040
	v_mul_f32_e32 v0, v63, v1
	v_cvt_pk_bf16_f32 v0, v0, v0
	ds_write_b16 v66, v0 offset:7104
	v_mov_b64_e32 v[0:1], s[42:43]
	v_mad_i64_i32 v[0:1], s[0:1], v2, s33, v[0:1]
	v_lshlrev_b32_e32 v2, 4, v64
	v_and_b32_e32 v160, 0xf0, v2
	v_lshl_add_u64 v[8:9], v[0:1], 0, v[160:161]
	v_lshlrev_b32_e32 v0, 8, v4
	s_waitcnt lgkmcnt(0)
	v_add3_u32 v14, v71, v160, v0
	ds_read_b128 v[0:3], v14
	v_mul_u32_u24_e32 v4, 0x1c00, v4
	v_lshlrev_b32_e32 v160, 1, v4
	ds_read_b128 v[4:7], v14 offset:1024
	v_lshl_add_u64 v[10:11], v[8:9], 0, v[160:161]
	s_waitcnt lgkmcnt(1)
	global_store_dwordx4 v[10:11], v[0:3], off
	s_nop 1
	v_add_co_u32_e32 v0, vcc, s47, v10
	s_nop 1
	v_addc_co_u32_e32 v1, vcc, 0, v11, vcc
	s_waitcnt lgkmcnt(0)
	global_store_dwordx4 v[0:1], v[4:7], off
	ds_read_b128 v[0:3], v14 offset:2048
	ds_read_b128 v[4:7], v14 offset:3072
	v_add_co_u32_e32 v12, vcc, s48, v10
	s_nop 1
	v_addc_co_u32_e32 v13, vcc, 0, v11, vcc
	s_waitcnt lgkmcnt(1)
	global_store_dwordx4 v[12:13], v[0:3], off
	s_nop 1
	v_add_co_u32_e32 v0, vcc, s49, v10
	s_nop 1
	v_addc_co_u32_e32 v1, vcc, 0, v11, vcc
	s_waitcnt lgkmcnt(0)
	global_store_dwordx4 v[0:1], v[4:7], off
	ds_read_b128 v[0:3], v14 offset:4096
	s_nop 0
	v_add_u32_e32 v4, 0x38000, v160
	v_mov_b32_e32 v5, v161
	v_lshl_add_u64 v[10:11], v[8:9], 0, v[4:5]
	ds_read_b128 v[4:7], v14 offset:5120
	s_waitcnt lgkmcnt(1)
	global_store_dwordx4 v[10:11], v[0:3], off
	v_add_u32_e32 v10, 0x54000, v160
	v_mov_b32_e32 v11, v161
	v_add_u32_e32 v0, 0x46000, v160
	v_mov_b32_e32 v1, v161
	v_lshl_add_u64 v[0:1], v[8:9], 0, v[0:1]
	s_waitcnt lgkmcnt(0)
	global_store_dwordx4 v[0:1], v[4:7], off
	ds_read_b128 v[0:3], v14 offset:6144
	ds_read_b128 v[4:7], v14 offset:7168
	v_lshl_add_u64 v[10:11], v[8:9], 0, v[10:11]
	v_add_u32_e32 v160, 0x62000, v160
	s_waitcnt lgkmcnt(1)
	global_store_dwordx4 v[10:11], v[0:3], off
	s_nop 1
	v_lshl_add_u64 v[0:1], v[8:9], 0, v[160:161]
	s_waitcnt lgkmcnt(0)
	global_store_dwordx4 v[0:1], v[4:7], off
	s_nop 0
	s_barrier
	s_cbranch_scc1 .LBB0_532

; __device__ __forceinline__ unsigned cvt_pk_bf16(float lo, float hi) { unsigned r; asm volatile("v_cvt_pk_bf16_f32 %0, %1, %2" : "=v"(r) : "v"(lo), "v"(hi)); return r; }
; __device__ __forceinline__ int crow(int r, int hi) { return (r & 3) + 8 * (r >> 2) + 4 * hi; }
;     ...
;         if (hib == 0) li2[r32b] = l_reg; asm volatile("s_waitcnt lgkmcnt(0)" ::: "memory");
;         __syncthreads();
;         bf16_t* stash = (bf16_t*)(lds + OFF_Q) + wid2 * 4096;
;         bf16_t* stg = (mode == 1) ? stash : ((bf16_t*)lds + wid2 * 4096);
; #pragma unroll
;         for (int r = 0; r < 16; ++r) { const int orow = crow(r, hib); const float rl = __builtin_amdgcn_rcpf(li2[orow]);
; #pragma unroll
;             for (int d0 = 0; d0 < 4; ++d0) { const float v = o[d0][r] * rl; stg[orow * 128 + d0 * 32 + r32b] = (bf16_t)(cvt_pk_bf16(v, v) & 0xffffu); } }
.LBB0_557:
	s_or_b64 exec, exec, s[0:1]
	v_lshrrev_b32_e32 v66, 3, v65
	v_and_b32_e32 v66, 4, v66
	v_lshl_add_u32 v68, v66, 2, v68
	s_waitcnt lgkmcnt(0)
	s_waitcnt lgkmcnt(0)
	s_barrier
	ds_read_b32 v69, v68
	v_ashrrev_i32_e32 v70, 6, v65
	v_lshlrev_b32_e32 v71, 13, v70
	v_add_u32_e32 v72, 0, v71
	v_lshlrev_b32_e32 v67, 1, v67
	s_waitcnt lgkmcnt(0)
	v_rcp_f32_e32 v69, v69
	v_lshlrev_b32_e32 v66, 8, v66
	v_add3_u32 v66, v72, v67, v66
	s_movk_i32 s0, 0x3800
	v_mul_f32_e32 v0, v0, v69
	v_cvt_pk_bf16_f32 v0, v0, v0
	ds_write_b16 v66, v0
	v_mul_f32_e32 v0, v16, v69
	v_cvt_pk_bf16_f32 v0, v0, v0
	ds_write_b16 v66, v0 offset:64
	v_mul_f32_e32 v0, v32, v69
	v_cvt_pk_bf16_f32 v0, v0, v0
	ds_write_b16 v66, v0 offset:128
	v_mul_f32_e32 v0, v48, v69
	v_cvt_pk_bf16_f32 v0, v0, v0
	ds_read_b32 v16, v68 offset:4
	ds_write_b16 v66, v0 offset:192
	s_add_i32 s54, s54, s15
	s_add_i32 s33, s33, s34
	s_cmpk_gt_i32 s54, 0x1ff
	s_waitcnt lgkmcnt(1)
	v_rcp_f32_e32 v16, v16
	s_nop 0
	v_mul_f32_e32 v0, v1, v16
	v_cvt_pk_bf16_f32 v0, v0, v0
	ds_write_b16 v66, v0 offset:256
	v_mul_f32_e32 v0, v17, v16
	v_cvt_pk_bf16_f32 v0, v0, v0
	ds_write_b16 v66, v0 offset:320
	v_mul_f32_e32 v0, v33, v16
	v_cvt_pk_bf16_f32 v0, v0, v0
	ds_write_b16 v66, v0 offset:384
	v_mul_f32_e32 v0, v49, v16
	v_cvt_pk_bf16_f32 v0, v0, v0
	ds_read_b32 v1, v68 offset:8
	ds_write_b16 v66, v0 offset:448
	s_waitcnt lgkmcnt(1)
	v_rcp_f32_e32 v1, v1
	s_nop 0
	v_mul_f32_e32 v0, v2, v1
	v_cvt_pk_bf16_f32 v0, v0, v0
	ds_write_b16 v66, v0 offset:512
	v_mul_f32_e32 v0, v18, v1
	v_cvt_pk_bf16_f32 v0, v0, v0
	ds_write_b16 v66, v0 offset:576
	v_mul_f32_e32 v0, v34, v1
	v_cvt_pk_bf16_f32 v0, v0, v0
	ds_write_b16 v66, v0 offset:640
	v_mul_f32_e32 v0, v50, v1
	v_cvt_pk_bf16_f32 v0, v0, v0
	ds_read_b32 v1, v68 offset:12
	ds_write_b16 v66, v0 offset:704
	s_waitcnt lgkmcnt(1)
	v_rcp_f32_e32 v1, v1
	s_nop 0
	v_mul_f32_e32 v0, v3, v1
	v_cvt_pk_bf16_f32 v0, v0, v0
	ds_write_b16 v66, v0 offset:768
	v_mul_f32_e32 v0, v19, v1
	v_cvt_pk_bf16_f32 v0, v0, v0
	ds_write_b16 v66, v0 offset:832
	v_mul_f32_e32 v0, v35, v1
	v_cvt_pk_bf16_f32 v0, v0, v0
	ds_write_b16 v66, v0 offset:896
	v_mul_f32_e32 v0, v51, v1
	v_cvt_pk_bf16_f32 v0, v0, v0
	ds_read_b32 v1, v68 offset:32
	ds_write_b16 v66, v0 offset:960
	s_waitcnt lgkmcnt(1)
	v_rcp_f32_e32 v1, v1
	s_nop 0
	v_mul_f32_e32 v0, v4, v1
	v_cvt_pk_bf16_f32 v0, v0, v0
	ds_write_b16 v66, v0 offset:2048
	v_mul_f32_e32 v0, v20, v1
	v_cvt_pk_bf16_f32 v0, v0, v0
	ds_write_b16 v66, v0 offset:2112
	v_mul_f32_e32 v0, v36, v1
	v_cvt_pk_bf16_f32 v0, v0, v0
	ds_write_b16 v66, v0 offset:2176
	v_mul_f32_e32 v0, v52, v1
	v_cvt_pk_bf16_f32 v0, v0, v0
	ds_read_b32 v1, v68 offset:36
	ds_write_b16 v66, v0 offset:2240
	s_waitcnt lgkmcnt(1)
	v_rcp_f32_e32 v1, v1
	s_nop 0
	v_mul_f32_e32 v0, v5, v1
	v_cvt_pk_bf16_f32 v0, v0, v0
	ds_write_b16 v66, v0 offset:2304
	v_mul_f32_e32 v0, v21, v1
	v_cvt_pk_bf16_f32 v0, v0, v0
	ds_write_b16 v66, v0 offset:2368
	v_mul_f32_e32 v0, v37, v1
	v_cvt_pk_bf16_f32 v0, v0, v0
	ds_write_b16 v66, v0 offset:2432
	v_mul_f32_e32 v0, v53, v1
	v_cvt_pk_bf16_f32 v0, v0, v0
	ds_read_b32 v1, v68 offset:40
	ds_write_b16 v66, v0 offset:2496
	s_waitcnt lgkmcnt(1)
	v_rcp_f32_e32 v1, v1
	s_nop 0
	v_mul_f32_e32 v0, v6, v1
	v_cvt_pk_bf16_f32 v0, v0, v0
	ds_write_b16 v66, v0 offset:2560
	v_mul_f32_e32 v0, v22, v1
	v_cvt_pk_bf16_f32 v0, v0, v0
	ds_write_b16 v66, v0 offset:2624
	v_mul_f32_e32 v0, v38, v1
	v_cvt_pk_bf16_f32 v0, v0, v0
	ds_write_b16 v66, v0 offset:2688
	v_mul_f32_e32 v0, v54, v1
	v_cvt_pk_bf16_f32 v0, v0, v0
	ds_read_b32 v1, v68 offset:44
	ds_write_b16 v66, v0 offset:2752
	s_waitcnt lgkmcnt(1)
	v_rcp_f32_e32 v1, v1
	s_nop 0
	v_mul_f32_e32 v0, v7, v1
	v_cvt_pk_bf16_f32 v0, v0, v0
	ds_write_b16 v66, v0 offset:2816
	v_mul_f32_e32 v0, v23, v1
	v_cvt_pk_bf16_f32 v0, v0, v0
	ds_write_b16 v66, v0 offset:2880
	v_mul_f32_e32 v0, v39, v1
	v_cvt_pk_bf16_f32 v0, v0, v0
	ds_write_b16 v66, v0 offset:2944
	v_mul_f32_e32 v0, v55, v1
	v_cvt_pk_bf16_f32 v0, v0, v0
	ds_read_b32 v1, v68 offset:64
	ds_write_b16 v66, v0 offset:3008
	v_lshrrev_b32_e32 v23, 4, v64
	v_lshlrev_b32_e32 v22, 8, v23
	s_waitcnt lgkmcnt(1)
	v_rcp_f32_e32 v1, v1
	s_nop 0
	v_mul_f32_e32 v0, v8, v1
	v_cvt_pk_bf16_f32 v0, v0, v0
	ds_write_b16 v66, v0 offset:4096
	v_mul_f32_e32 v0, v24, v1
	v_cvt_pk_bf16_f32 v0, v0, v0
	ds_write_b16 v66, v0 offset:4160
	v_mul_f32_e32 v0, v40, v1
	v_cvt_pk_bf16_f32 v0, v0, v0
	ds_write_b16 v66, v0 offset:4224
	v_mul_f32_e32 v0, v56, v1
	v_cvt_pk_bf16_f32 v0, v0, v0
	ds_read_b32 v1, v68 offset:68
	ds_write_b16 v66, v0 offset:4288
	s_waitcnt lgkmcnt(1)
	v_rcp_f32_e32 v1, v1
	s_nop 0
	v_mul_f32_e32 v0, v9, v1
	v_cvt_pk_bf16_f32 v0, v0, v0
	ds_write_b16 v66, v0 offset:4352
	v_mul_f32_e32 v0, v25, v1
	v_cvt_pk_bf16_f32 v0, v0, v0
	ds_write_b16 v66, v0 offset:4416
	v_mul_f32_e32 v0, v41, v1
	v_cvt_pk_bf16_f32 v0, v0, v0
	ds_write_b16 v66, v0 offset:4480
	v_mul_f32_e32 v0, v57, v1
	v_cvt_pk_bf16_f32 v0, v0, v0
	ds_read_b32 v1, v68 offset:72
	ds_write_b16 v66, v0 offset:4544
	s_waitcnt lgkmcnt(1)
	v_rcp_f32_e32 v1, v1
	s_nop 0
	v_mul_f32_e32 v0, v10, v1
	v_cvt_pk_bf16_f32 v0, v0, v0
	ds_write_b16 v66, v0 offset:4608
	v_mul_f32_e32 v0, v26, v1
	v_cvt_pk_bf16_f32 v0, v0, v0
	ds_write_b16 v66, v0 offset:4672
	v_mul_f32_e32 v0, v42, v1
	v_cvt_pk_bf16_f32 v0, v0, v0
	ds_write_b16 v66, v0 offset:4736
	v_mul_f32_e32 v0, v58, v1
	v_cvt_pk_bf16_f32 v0, v0, v0
	ds_read_b32 v1, v68 offset:76
	ds_write_b16 v66, v0 offset:4800
	s_waitcnt lgkmcnt(1)
; __device__ __forceinline__ unsigned cvt_pk_bf16(float lo, float hi) { unsigned r; asm volatile("v_cvt_pk_bf16_f32 %0, %1, %2" : "=v"(r) : "v"(lo), "v"(hi)); return r; }
; __device__ __forceinline__ int crow(int r, int hi) { return (r & 3) + 8 * (r >> 2) + 4 * hi; }
;     ...
;         for (int r = 0; r < 16; ++r) { const int orow = crow(r, hib); const float rl = __builtin_amdgcn_rcpf(li2[orow]);
; #pragma unroll
;             for (int d0 = 0; d0 < 4; ++d0) { const float v = o[d0][r] * rl; stg[orow * 128 + d0 * 32 + r32b] = (bf16_t)(cvt_pk_bf16(v, v) & 0xffffu); } }
;         asm volatile("s_waitcnt lgkmcnt(0)" ::: "memory");
;         if (mode != 1) {
;             bf16_t* Ow = Ob + (size_t)(wid2 * QBLK) * LDO;
;             const int ch = lane2 & 15;
;             float gg[8];
;             if (mode == 2) {
; #pragma unroll
;                 for (int e = 0; e < 8; ++e) gg[e] = sg[ch * 8 + e] * 0.8f; }
; #pragma unroll
;             for (int i = 0; i < 8; ++i) { const int row = i * 4 + (lane2 >> 4); u32x4 v = *(const u32x4*)(stg + row * 128 + ch * 8);
;                 if (mode == 2) { const u32x4 v0 = *(const u32x4*)(stash + row * 128 + ch * 8); float x0[8], x1[8]; unpack8(v0, x0); unpack8(v, x1); float ss = 0.f;
; #pragma unroll
;                     for (int e = 0; e < 8; ++e) { x0[e] = x0[e] - lam * x1[e]; ss += x0[e] * x0[e]; }
;                     ss += __shfl_xor(ss, 1); ss += __shfl_xor(ss, 2); ss += __shfl_xor(ss, 4); ss += __shfl_xor(ss, 8);
;                     const float rstd = rsqrtf(ss * (1.0f / 128) + EPS);
; #pragma unroll
;                     for (int e = 0; e < 8; ++e) x0[e] = x0[e] * rstd * gg[e];
;                     v = pack8(x0); }
;                 *(u32x4*)(Ow + (size_t)row * LDO + ch * 8) = v; }
	v_rcp_f32_e32 v1, v1
	s_nop 0
	v_mul_f32_e32 v0, v11, v1
	v_cvt_pk_bf16_f32 v0, v0, v0
	ds_write_b16 v66, v0 offset:4864
	v_mul_f32_e32 v0, v27, v1
	v_cvt_pk_bf16_f32 v0, v0, v0
	ds_write_b16 v66, v0 offset:4928
	v_mul_f32_e32 v0, v43, v1
	v_cvt_pk_bf16_f32 v0, v0, v0
	ds_write_b16 v66, v0 offset:4992
	v_mul_f32_e32 v0, v59, v1
	v_cvt_pk_bf16_f32 v0, v0, v0
	ds_read_b32 v1, v68 offset:96
	ds_write_b16 v66, v0 offset:5056
	s_waitcnt lgkmcnt(1)
	v_rcp_f32_e32 v1, v1
	s_nop 0
	v_mul_f32_e32 v0, v12, v1
	v_cvt_pk_bf16_f32 v0, v0, v0
	ds_write_b16 v66, v0 offset:6144
	v_mul_f32_e32 v0, v28, v1
	v_cvt_pk_bf16_f32 v0, v0, v0
	ds_write_b16 v66, v0 offset:6208
	v_mul_f32_e32 v0, v44, v1
	v_cvt_pk_bf16_f32 v0, v0, v0
	ds_write_b16 v66, v0 offset:6272
	v_mul_f32_e32 v0, v60, v1
	v_cvt_pk_bf16_f32 v0, v0, v0
	ds_read_b32 v1, v68 offset:100
	ds_write_b16 v66, v0 offset:6336
	s_waitcnt lgkmcnt(1)
	v_rcp_f32_e32 v1, v1
	s_nop 0
	v_mul_f32_e32 v0, v13, v1
	v_cvt_pk_bf16_f32 v0, v0, v0
	ds_write_b16 v66, v0 offset:6400
	v_mul_f32_e32 v0, v29, v1
	v_cvt_pk_bf16_f32 v0, v0, v0
	ds_write_b16 v66, v0 offset:6464
	v_mul_f32_e32 v0, v45, v1
	v_cvt_pk_bf16_f32 v0, v0, v0
	ds_write_b16 v66, v0 offset:6528
	v_mul_f32_e32 v0, v61, v1
	v_cvt_pk_bf16_f32 v0, v0, v0
	ds_read_b32 v1, v68 offset:104
	ds_write_b16 v66, v0 offset:6592
	s_waitcnt lgkmcnt(1)
	v_rcp_f32_e32 v1, v1
	s_nop 0
	v_mul_f32_e32 v0, v14, v1
	v_cvt_pk_bf16_f32 v0, v0, v0
	ds_write_b16 v66, v0 offset:6656
	v_mul_f32_e32 v0, v30, v1
	v_cvt_pk_bf16_f32 v0, v0, v0
	ds_write_b16 v66, v0 offset:6720
	v_mul_f32_e32 v0, v46, v1
	v_cvt_pk_bf16_f32 v0, v0, v0
	ds_write_b16 v66, v0 offset:6784
	v_mul_f32_e32 v0, v62, v1
	v_cvt_pk_bf16_f32 v0, v0, v0
	ds_read_b32 v1, v68 offset:108
	ds_write_b16 v66, v0 offset:6848
	s_waitcnt lgkmcnt(1)
	v_rcp_f32_e32 v1, v1
	s_nop 0
	v_mul_f32_e32 v0, v15, v1
	v_cvt_pk_bf16_f32 v0, v0, v0
	ds_write_b16 v66, v0 offset:6912
	v_mul_f32_e32 v0, v31, v1
	v_cvt_pk_bf16_f32 v0, v0, v0
	ds_write_b16 v66, v0 offset:6976
	v_mul_f32_e32 v0, v47, v1
	v_cvt_pk_bf16_f32 v0, v0, v0
	ds_write_b16 v66, v0 offset:7040
	v_mul_f32_e32 v0, v63, v1
	v_cvt_pk_bf16_f32 v0, v0, v0
	ds_write_b16 v66, v0 offset:7104
	v_lshlrev_b32_e32 v0, 3, v65
	v_and_b32_e32 v0, 0x78, v0
	s_waitcnt lgkmcnt(0)
	v_lshlrev_b32_e32 v12, 2, v0
	global_load_dwordx4 v[4:7], v12, s[16:17]
	v_lshlrev_b32_e32 v134, 1, v0
	global_load_dwordx4 v[12:15], v12, s[16:17] offset:16
	v_add_u32_e32 v20, v72, v134
	v_add3_u32 v21, s48, v71, v134
	v_add_u32_e32 v0, v21, v22
	v_add_u32_e32 v8, v20, v22
	ds_read_b128 v[0:3], v0
	ds_read_b128 v[8:11], v8
	s_waitcnt lgkmcnt(1)
	v_lshlrev_b32_e32 v16, 16, v0
	v_and_b32_e32 v0, 0xffff0000, v0
	s_waitcnt lgkmcnt(0)
	v_lshlrev_b32_e32 v17, 16, v8
	v_and_b32_e32 v8, 0xffff0000, v8
	v_fma_f32 v19, -v128, v8, v0
	v_and_b32_e32 v0, 0xffff0000, v1
	v_lshlrev_b32_e32 v1, 16, v1
	v_and_b32_e32 v8, 0xffff0000, v9
	v_lshlrev_b32_e32 v9, 16, v9
	v_fma_f32 v17, -v128, v17, v16
	v_mul_f32_e32 v16, v19, v19
	v_pk_fma_f32 v[8:9], v[128:129], v[8:9], v[0:1] neg_lo:[1,0,0] neg_hi:[1,0,0]
	v_fmac_f32_e32 v16, v17, v17
	v_pk_mul_f32 v[0:1], v[8:9], v[8:9]
	v_and_b32_e32 v24, 0xffff0000, v10
	v_add_f32_e32 v1, v1, v16
	v_add_f32_e32 v16, v0, v1
	v_and_b32_e32 v0, 0xffff0000, v2
	v_lshlrev_b32_e32 v1, 16, v2
	v_lshlrev_b32_e32 v25, 16, v10
	v_pk_fma_f32 v[24:25], v[128:129], v[24:25], v[0:1] neg_lo:[1,0,0] neg_hi:[1,0,0]
	v_and_b32_e32 v2, 0xffff0000, v11
	v_pk_mul_f32 v[0:1], v[24:25], v[24:25]
	s_waitcnt vmcnt(1)
	v_mov_b32_e32 v18, v5
	v_add_f32_e32 v1, v1, v16
	v_add_f32_e32 v10, v0, v1
	v_and_b32_e32 v0, 0xffff0000, v3
	v_lshlrev_b32_e32 v1, 16, v3
	v_lshlrev_b32_e32 v3, 16, v11
	v_pk_fma_f32 v[26:27], v[128:129], v[2:3], v[0:1] neg_lo:[1,0,0] neg_hi:[1,0,0]
	v_mov_b32_e32 v16, v4
	v_pk_mul_f32 v[0:1], v[26:27], v[26:27]
	v_mov_b32_e32 v4, v6
	v_add_f32_e32 v1, v1, v10
	v_add_f32_e32 v0, v0, v1
	ds_bpermute_b32 v1, v220, v0
	v_mov_b32_e32 v5, v9
	v_mov_b32_e32 v6, v7
	v_mov_b32_e32 v7, v8
	s_waitcnt vmcnt(0)
	v_mov_b32_e32 v8, v12
	s_waitcnt lgkmcnt(0)
	v_add_f32_e32 v0, v0, v1
	ds_bpermute_b32 v1, v221, v0
	v_mov_b32_e32 v9, v25
	v_mov_b32_e32 v10, v13
	v_mov_b32_e32 v11, v24
	v_mov_b32_e32 v12, v14
	s_waitcnt lgkmcnt(0)
	v_add_f32_e32 v0, v0, v1
	ds_bpermute_b32 v1, v222, v0
	v_mov_b32_e32 v13, v27
	v_mov_b32_e32 v14, v15
	v_mov_b32_e32 v15, v26
	s_waitcnt lgkmcnt(0)
	v_add_f32_e32 v0, v0, v1
	ds_bpermute_b32 v1, v223, v0
	s_waitcnt lgkmcnt(0)
	v_add_f32_e32 v0, v0, v1
	v_fmamk_f32 v0, v0, 0x3c000000, v209
	v_mul_f32_e32 v1, 0x4b800000, v0
	v_cmp_gt_f32_e32 vcc, s50, v0
	s_nop 1
	v_cndmask_b32_e32 v0, v0, v1, vcc
	v_rsq_f32_e32 v0, v0
	s_nop 0
	v_mul_f32_e32 v1, 0x45800000, v0
	v_cndmask_b32_e32 v141, v0, v1, vcc
	v_pk_mul_f32 v[0:1], v[16:17], v[140:141]
	v_pk_mul_f32 v[2:3], v[18:19], v[140:141]
	v_mul_f32_e32 v1, v0, v1
	v_mul_f32_e32 v3, v2, v3
	v_cvt_pk_bf16_f32 v24, v1, v3
	v_or_b32_e32 v1, 0x400, v22
	v_pk_mul_f32 v[4:5], v[4:5], v[140:141]
	v_pk_mul_f32 v[6:7], v[6:7], v[140:141]
	v_pk_mul_f32 v[8:9], v[8:9], v[140:141]
	v_pk_mul_f32 v[10:11], v[10:11], v[140:141]
	v_pk_mul_f32 v[12:13], v[12:13], v[140:141]
	v_pk_mul_f32 v[14:15], v[14:15], v[140:141]
	v_add_u32_e32 v3, v21, v1
	v_add_u32_e32 v1, v20, v1
	v_mul_f32_e32 v5, v4, v5
	v_mul_f32_e32 v7, v6, v7
	v_mul_f32_e32 v9, v8, v9
	v_mul_f32_e32 v11, v10, v11
	v_mul_f32_e32 v13, v12, v13
	v_mul_f32_e32 v15, v14, v15
	v_cvt_pk_bf16_f32 v25, v5, v7
	v_cvt_pk_bf16_f32 v26, v9, v11
	v_cvt_pk_bf16_f32 v27, v13, v15
	ds_read_b128 v[16:19], v3
	ds_read_b128 v[28:31], v1
	v_lshlrev_b32_e32 v9, 5, v70
	s_waitcnt lgkmcnt(1)
	v_and_b32_e32 v3, 0xffff0000, v16
	s_waitcnt lgkmcnt(0)
;     ...
;             for (int i = 0; i < 8; ++i) { const int row = i * 4 + (lane2 >> 4); u32x4 v = *(const u32x4*)(stg + row * 128 + ch * 8);
;                 if (mode == 2) { const u32x4 v0 = *(const u32x4*)(stash + row * 128 + ch * 8); float x0[8], x1[8]; unpack8(v0, x0); unpack8(v, x1); float ss = 0.f;
; #pragma unroll
;                     for (int e = 0; e < 8; ++e) { x0[e] = x0[e] - lam * x1[e]; ss += x0[e] * x0[e]; }
;                     ss += __shfl_xor(ss, 1); ss += __shfl_xor(ss, 2); ss += __shfl_xor(ss, 4); ss += __shfl_xor(ss, 8);
;                     const float rstd = rsqrtf(ss * (1.0f / 128) + EPS);
; #pragma unroll
;                     for (int e = 0; e < 8; ++e) x0[e] = x0[e] * rstd * gg[e];
;                     v = pack8(x0); }
;                 *(u32x4*)(Ow + (size_t)row * LDO + ch * 8) = v; }
	v_and_b32_e32 v7, 0xffff0000, v28
	v_lshlrev_b32_e32 v1, 16, v16
	v_lshlrev_b32_e32 v5, 16, v28
	v_fma_f32 v3, -v128, v7, v3
	v_and_b32_e32 v16, 0xffff0000, v17
	v_lshlrev_b32_e32 v17, 16, v17
	v_and_b32_e32 v28, 0xffff0000, v29
	v_lshlrev_b32_e32 v29, 16, v29
	v_fma_f32 v1, -v128, v5, v1
	v_mul_f32_e32 v5, v3, v3
	v_pk_fma_f32 v[28:29], v[128:129], v[28:29], v[16:17] neg_lo:[1,0,0] neg_hi:[1,0,0]
	v_fmac_f32_e32 v5, v1, v1
	v_pk_mul_f32 v[16:17], v[28:29], v[28:29]
	v_and_b32_e32 v32, 0xffff0000, v30
	v_add_f32_e32 v5, v17, v5
	v_add_f32_e32 v5, v16, v5
	v_and_b32_e32 v16, 0xffff0000, v18
	v_lshlrev_b32_e32 v17, 16, v18
	v_lshlrev_b32_e32 v33, 16, v30
	v_pk_fma_f32 v[32:33], v[128:129], v[32:33], v[16:17] neg_lo:[1,0,0] neg_hi:[1,0,0]
	v_and_b32_e32 v18, 0xffff0000, v31
	v_pk_mul_f32 v[16:17], v[32:33], v[32:33]
	s_nop 0
	v_add_f32_e32 v5, v17, v5
	v_add_f32_e32 v5, v16, v5
	v_and_b32_e32 v16, 0xffff0000, v19
	v_lshlrev_b32_e32 v17, 16, v19
	v_lshlrev_b32_e32 v19, 16, v31
	v_pk_fma_f32 v[30:31], v[128:129], v[18:19], v[16:17] neg_lo:[1,0,0] neg_hi:[1,0,0]
	s_nop 0
	v_pk_mul_f32 v[16:17], v[30:31], v[30:31]
	s_nop 0
	v_add_f32_e32 v5, v17, v5
	v_add_f32_e32 v5, v16, v5
	ds_bpermute_b32 v7, v220, v5
	v_mov_b64_e32 v[16:17], s[4:5]
	v_mad_i64_i32 v[16:17], s[0:1], v9, s0, v[16:17]
	v_mul_u32_u24_e32 v9, 0x1c00, v23
	s_waitcnt lgkmcnt(0)
	v_add_f32_e32 v5, v5, v7
	ds_bpermute_b32 v7, v221, v5
	v_lshl_add_u64 v[16:17], v[16:17], 0, v[134:135]
	v_lshlrev_b32_e32 v134, 1, v9
	v_lshl_add_u64 v[18:19], v[16:17], 0, v[134:135]
	global_store_dwordx4 v[18:19], v[24:27], off
	s_waitcnt lgkmcnt(0)
	v_add_f32_e32 v5, v5, v7
	ds_bpermute_b32 v7, v222, v5
	s_waitcnt lgkmcnt(0)
	v_add_f32_e32 v5, v5, v7
	ds_bpermute_b32 v7, v223, v5
	s_waitcnt lgkmcnt(0)
	v_add_f32_e32 v5, v5, v7
	v_fmamk_f32 v5, v5, 0x3c000000, v209
	v_mul_f32_e32 v7, 0x4b800000, v5
	v_cmp_gt_f32_e32 vcc, s50, v5
	s_nop 1
	v_cndmask_b32_e32 v5, v5, v7, vcc
	v_rsq_f32_e32 v5, v5
	s_nop 0
	v_mul_f32_e32 v7, 0x45800000, v5
	v_cndmask_b32_e32 v5, v5, v7, vcc
	v_mul_f32_e32 v1, v1, v5
	v_mul_f32_e32 v1, v0, v1
	v_mul_f32_e32 v3, v3, v5
	v_mul_f32_e32 v3, v2, v3
	v_cvt_pk_bf16_f32 v24, v1, v3
	v_or_b32_e32 v1, 0x800, v22
	v_mul_f32_e32 v7, v29, v5
	v_mul_f32_e32 v9, v28, v5
	v_mul_f32_e32 v11, v33, v5
	v_mul_f32_e32 v13, v32, v5
	v_mul_f32_e32 v15, v31, v5
	v_mul_f32_e32 v5, v30, v5
	v_add_u32_e32 v3, v21, v1
	v_add_u32_e32 v1, v20, v1
	v_mul_f32_e32 v7, v4, v7
	v_mul_f32_e32 v9, v6, v9
	v_mul_f32_e32 v11, v8, v11
	v_mul_f32_e32 v13, v10, v13
	v_mul_f32_e32 v15, v12, v15
	v_mul_f32_e32 v5, v14, v5
	v_cvt_pk_bf16_f32 v25, v7, v9
	v_cvt_pk_bf16_f32 v26, v11, v13
	v_cvt_pk_bf16_f32 v27, v15, v5
	ds_read_b128 v[28:31], v3
	ds_read_b128 v[32:35], v1
	s_waitcnt lgkmcnt(1)
	v_and_b32_e32 v3, 0xffff0000, v28
	s_waitcnt lgkmcnt(0)
	v_and_b32_e32 v7, 0xffff0000, v32
	v_lshlrev_b32_e32 v1, 16, v28
	v_lshlrev_b32_e32 v5, 16, v32
	v_fma_f32 v3, -v128, v7, v3
	v_and_b32_e32 v28, 0xffff0000, v29
	v_lshlrev_b32_e32 v29, 16, v29
	v_and_b32_e32 v32, 0xffff0000, v33
	v_lshlrev_b32_e32 v33, 16, v33
	v_fma_f32 v1, -v128, v5, v1
	v_mul_f32_e32 v5, v3, v3
	v_pk_fma_f32 v[28:29], v[128:129], v[32:33], v[28:29] neg_lo:[1,0,0] neg_hi:[1,0,0]
	v_fmac_f32_e32 v5, v1, v1
	v_pk_mul_f32 v[32:33], v[28:29], v[28:29]
	v_and_b32_e32 v36, 0xffff0000, v34
	v_add_f32_e32 v5, v33, v5
	v_add_f32_e32 v5, v32, v5
	v_and_b32_e32 v32, 0xffff0000, v30
	v_lshlrev_b32_e32 v33, 16, v30
	v_lshlrev_b32_e32 v37, 16, v34
	v_pk_fma_f32 v[32:33], v[128:129], v[36:37], v[32:33] neg_lo:[1,0,0] neg_hi:[1,0,0]
	v_and_b32_e32 v30, 0xffff0000, v31
	v_pk_mul_f32 v[36:37], v[32:33], v[32:33]
	v_lshlrev_b32_e32 v31, 16, v31
	v_and_b32_e32 v34, 0xffff0000, v35
	v_lshlrev_b32_e32 v35, 16, v35
	v_add_f32_e32 v5, v37, v5
	v_pk_fma_f32 v[30:31], v[128:129], v[34:35], v[30:31] neg_lo:[1,0,0] neg_hi:[1,0,0]
	v_add_f32_e32 v5, v36, v5
	v_pk_mul_f32 v[34:35], v[30:31], v[30:31]
	s_nop 0
	v_add_f32_e32 v5, v35, v5
	v_add_f32_e32 v5, v34, v5
	ds_bpermute_b32 v7, v220, v5
	v_add_co_u32_e64 v34, s[4:5], s51, v18
	s_waitcnt lgkmcnt(0)
	v_add_f32_e32 v5, v5, v7
	ds_bpermute_b32 v7, v221, v5
	v_addc_co_u32_e64 v35, s[4:5], 0, v19, s[4:5]
	global_store_dwordx4 v[34:35], v[24:27], off
	s_waitcnt lgkmcnt(0)
	v_add_f32_e32 v5, v5, v7
	ds_bpermute_b32 v7, v222, v5
	s_waitcnt lgkmcnt(0)
	v_add_f32_e32 v5, v5, v7
	ds_bpermute_b32 v7, v223, v5
	s_waitcnt lgkmcnt(0)
	v_add_f32_e32 v5, v5, v7
	v_fmamk_f32 v5, v5, 0x3c000000, v209
	v_mul_f32_e32 v7, 0x4b800000, v5
	v_cmp_gt_f32_e32 vcc, s50, v5
	s_nop 1
	v_cndmask_b32_e32 v5, v5, v7, vcc
	v_rsq_f32_e32 v5, v5
	s_nop 0
	v_mul_f32_e32 v7, 0x45800000, v5
	v_cndmask_b32_e32 v5, v5, v7, vcc
	v_mul_f32_e32 v1, v1, v5
	v_mul_f32_e32 v1, v0, v1
	v_mul_f32_e32 v3, v3, v5
	v_mul_f32_e32 v3, v2, v3
	v_cvt_pk_bf16_f32 v24, v1, v3
	v_or_b32_e32 v1, 0xc00, v22
	v_mul_f32_e32 v7, v29, v5
	v_mul_f32_e32 v9, v28, v5
	v_mul_f32_e32 v11, v33, v5
	v_mul_f32_e32 v13, v32, v5
	v_mul_f32_e32 v15, v31, v5
	v_mul_f32_e32 v5, v30, v5
	v_add_u32_e32 v3, v21, v1
	v_add_u32_e32 v1, v20, v1
	v_mul_f32_e32 v7, v4, v7
	v_mul_f32_e32 v9, v6, v9
	v_mul_f32_e32 v11, v8, v11
	v_mul_f32_e32 v13, v10, v13
	v_mul_f32_e32 v15, v12, v15
	v_mul_f32_e32 v5, v14, v5
	v_cvt_pk_bf16_f32 v25, v7, v9
	v_cvt_pk_bf16_f32 v26, v11, v13
	v_cvt_pk_bf16_f32 v27, v15, v5
	ds_read_b128 v[28:31], v3
	ds_read_b128 v[32:35], v1
	s_waitcnt lgkmcnt(1)
	v_and_b32_e32 v3, 0xffff0000, v28
	s_waitcnt lgkmcnt(0)
;     ...
;             for (int i = 0; i < 8; ++i) { const int row = i * 4 + (lane2 >> 4); u32x4 v = *(const u32x4*)(stg + row * 128 + ch * 8);
;                 if (mode == 2) { const u32x4 v0 = *(const u32x4*)(stash + row * 128 + ch * 8); float x0[8], x1[8]; unpack8(v0, x0); unpack8(v, x1); float ss = 0.f;
; #pragma unroll
;                     for (int e = 0; e < 8; ++e) { x0[e] = x0[e] - lam * x1[e]; ss += x0[e] * x0[e]; }
;                     ss += __shfl_xor(ss, 1); ss += __shfl_xor(ss, 2); ss += __shfl_xor(ss, 4); ss += __shfl_xor(ss, 8);
;                     const float rstd = rsqrtf(ss * (1.0f / 128) + EPS);
; #pragma unroll
;                     for (int e = 0; e < 8; ++e) x0[e] = x0[e] * rstd * gg[e];
;                     v = pack8(x0); }
;                 *(u32x4*)(Ow + (size_t)row * LDO + ch * 8) = v; }
	v_and_b32_e32 v7, 0xffff0000, v32
	v_lshlrev_b32_e32 v1, 16, v28
	v_lshlrev_b32_e32 v5, 16, v32
	v_fma_f32 v3, -v128, v7, v3
	v_and_b32_e32 v28, 0xffff0000, v29
	v_lshlrev_b32_e32 v29, 16, v29
	v_and_b32_e32 v32, 0xffff0000, v33
	v_lshlrev_b32_e32 v33, 16, v33
	v_fma_f32 v1, -v128, v5, v1
	v_mul_f32_e32 v5, v3, v3
	v_pk_fma_f32 v[28:29], v[128:129], v[32:33], v[28:29] neg_lo:[1,0,0] neg_hi:[1,0,0]
	v_fmac_f32_e32 v5, v1, v1
	v_pk_mul_f32 v[32:33], v[28:29], v[28:29]
	v_and_b32_e32 v36, 0xffff0000, v34
	v_add_f32_e32 v5, v33, v5
	v_add_f32_e32 v5, v32, v5
	v_and_b32_e32 v32, 0xffff0000, v30
	v_lshlrev_b32_e32 v33, 16, v30
	v_lshlrev_b32_e32 v37, 16, v34
	v_pk_fma_f32 v[32:33], v[128:129], v[36:37], v[32:33] neg_lo:[1,0,0] neg_hi:[1,0,0]
	v_and_b32_e32 v30, 0xffff0000, v31
	v_pk_mul_f32 v[36:37], v[32:33], v[32:33]
	v_lshlrev_b32_e32 v31, 16, v31
	v_and_b32_e32 v34, 0xffff0000, v35
	v_lshlrev_b32_e32 v35, 16, v35
	v_add_f32_e32 v5, v37, v5
	v_pk_fma_f32 v[30:31], v[128:129], v[34:35], v[30:31] neg_lo:[1,0,0] neg_hi:[1,0,0]
	v_add_f32_e32 v5, v36, v5
	v_pk_mul_f32 v[34:35], v[30:31], v[30:31]
	s_nop 0
	v_add_f32_e32 v5, v35, v5
	v_add_f32_e32 v5, v34, v5
	ds_bpermute_b32 v7, v220, v5
	v_add_co_u32_e64 v34, s[4:5], s52, v18
	s_waitcnt lgkmcnt(0)
	v_add_f32_e32 v5, v5, v7
	ds_bpermute_b32 v7, v221, v5
	v_addc_co_u32_e64 v35, s[4:5], 0, v19, s[4:5]
	global_store_dwordx4 v[34:35], v[24:27], off
	v_add_co_u32_e64 v18, s[4:5], s53, v18
	s_waitcnt lgkmcnt(0)
	v_add_f32_e32 v5, v5, v7
	ds_bpermute_b32 v7, v222, v5
	v_addc_co_u32_e64 v19, s[4:5], 0, v19, s[4:5]
	s_waitcnt lgkmcnt(0)
	v_add_f32_e32 v5, v5, v7
	ds_bpermute_b32 v7, v223, v5
	s_waitcnt lgkmcnt(0)
	v_add_f32_e32 v5, v5, v7
	v_fmamk_f32 v5, v5, 0x3c000000, v209
	v_mul_f32_e32 v7, 0x4b800000, v5
	v_cmp_gt_f32_e32 vcc, s50, v5
	s_nop 1
	v_cndmask_b32_e32 v5, v5, v7, vcc
	v_rsq_f32_e32 v5, v5
	s_nop 0
	v_mul_f32_e32 v7, 0x45800000, v5
	v_cndmask_b32_e32 v5, v5, v7, vcc
	v_mul_f32_e32 v1, v1, v5
	v_mul_f32_e32 v1, v0, v1
	v_mul_f32_e32 v3, v3, v5
	v_mul_f32_e32 v3, v2, v3
	v_cvt_pk_bf16_f32 v24, v1, v3
	v_or_b32_e32 v1, 0x1000, v22
	v_mul_f32_e32 v7, v29, v5
	v_mul_f32_e32 v9, v28, v5
	v_mul_f32_e32 v11, v33, v5
	v_mul_f32_e32 v13, v32, v5
	v_mul_f32_e32 v15, v31, v5
	v_mul_f32_e32 v5, v30, v5
	v_add_u32_e32 v3, v21, v1
	v_add_u32_e32 v1, v20, v1
	v_mul_f32_e32 v7, v4, v7
	v_mul_f32_e32 v9, v6, v9
	v_mul_f32_e32 v11, v8, v11
	v_mul_f32_e32 v13, v10, v13
	v_mul_f32_e32 v15, v12, v15
	v_mul_f32_e32 v5, v14, v5
	v_cvt_pk_bf16_f32 v25, v7, v9
	v_cvt_pk_bf16_f32 v26, v11, v13
	v_cvt_pk_bf16_f32 v27, v15, v5
	ds_read_b128 v[28:31], v3
	ds_read_b128 v[32:35], v1
	global_store_dwordx4 v[18:19], v[24:27], off
	s_waitcnt lgkmcnt(1)
	v_and_b32_e32 v3, 0xffff0000, v28
	s_waitcnt lgkmcnt(0)
	v_and_b32_e32 v7, 0xffff0000, v32
	v_lshlrev_b32_e32 v1, 16, v28
	v_lshlrev_b32_e32 v5, 16, v32
	v_fma_f32 v3, -v128, v7, v3
	v_and_b32_e32 v28, 0xffff0000, v29
	v_lshlrev_b32_e32 v29, 16, v29
	v_and_b32_e32 v32, 0xffff0000, v33
	v_lshlrev_b32_e32 v33, 16, v33
	v_fma_f32 v1, -v128, v5, v1
	v_mul_f32_e32 v5, v3, v3
	v_pk_fma_f32 v[28:29], v[128:129], v[32:33], v[28:29] neg_lo:[1,0,0] neg_hi:[1,0,0]
	v_fmac_f32_e32 v5, v1, v1
	v_pk_mul_f32 v[32:33], v[28:29], v[28:29]
	v_and_b32_e32 v36, 0xffff0000, v34
	v_add_f32_e32 v5, v33, v5
	v_add_f32_e32 v5, v32, v5
	v_and_b32_e32 v32, 0xffff0000, v30
	v_lshlrev_b32_e32 v33, 16, v30
	v_lshlrev_b32_e32 v37, 16, v34
	v_pk_fma_f32 v[32:33], v[128:129], v[36:37], v[32:33] neg_lo:[1,0,0] neg_hi:[1,0,0]
	v_and_b32_e32 v30, 0xffff0000, v31
	v_pk_mul_f32 v[36:37], v[32:33], v[32:33]
	v_lshlrev_b32_e32 v31, 16, v31
	v_and_b32_e32 v34, 0xffff0000, v35
	v_lshlrev_b32_e32 v35, 16, v35
	v_add_f32_e32 v5, v37, v5
	v_pk_fma_f32 v[30:31], v[128:129], v[34:35], v[30:31] neg_lo:[1,0,0] neg_hi:[1,0,0]
	v_add_f32_e32 v5, v36, v5
	v_pk_mul_f32 v[34:35], v[30:31], v[30:31]
	s_nop 0
	v_add_f32_e32 v5, v35, v5
	v_add_f32_e32 v5, v34, v5
	ds_bpermute_b32 v7, v220, v5
	s_waitcnt lgkmcnt(0)
	v_add_f32_e32 v5, v5, v7
	ds_bpermute_b32 v7, v221, v5
	s_waitcnt lgkmcnt(0)
	v_add_f32_e32 v5, v5, v7
	ds_bpermute_b32 v7, v222, v5
	s_waitcnt lgkmcnt(0)
	v_add_f32_e32 v5, v5, v7
	ds_bpermute_b32 v7, v223, v5
	s_waitcnt lgkmcnt(0)
	v_add_f32_e32 v5, v5, v7
	v_fmamk_f32 v5, v5, 0x3c000000, v209
	v_mul_f32_e32 v7, 0x4b800000, v5
	v_cmp_gt_f32_e32 vcc, s50, v5
	s_nop 1
	v_cndmask_b32_e32 v5, v5, v7, vcc
	v_rsq_f32_e32 v5, v5
	s_nop 0
	v_mul_f32_e32 v7, 0x45800000, v5
	v_cndmask_b32_e32 v5, v5, v7, vcc
	v_mul_f32_e32 v1, v1, v5
	v_mul_f32_e32 v1, v0, v1
	v_mul_f32_e32 v3, v3, v5
	v_mul_f32_e32 v3, v2, v3
	v_cvt_pk_bf16_f32 v24, v1, v3
	v_or_b32_e32 v1, 0x1400, v22
	v_mul_f32_e32 v7, v29, v5
	v_mul_f32_e32 v9, v28, v5
	v_mul_f32_e32 v11, v33, v5
	v_mul_f32_e32 v13, v32, v5
	v_mul_f32_e32 v15, v31, v5
	v_mul_f32_e32 v5, v30, v5
	v_add_u32_e32 v3, v21, v1
	v_add_u32_e32 v1, v20, v1
	v_mul_f32_e32 v7, v4, v7
	v_mul_f32_e32 v9, v6, v9
	v_mul_f32_e32 v11, v8, v11
	v_mul_f32_e32 v13, v10, v13
	v_mul_f32_e32 v15, v12, v15
	v_mul_f32_e32 v5, v14, v5
	v_cvt_pk_bf16_f32 v25, v7, v9
	v_cvt_pk_bf16_f32 v26, v11, v13
	v_cvt_pk_bf16_f32 v27, v15, v5
	ds_read_b128 v[28:31], v3
	ds_read_b128 v[32:35], v1
	s_waitcnt lgkmcnt(1)
	v_and_b32_e32 v3, 0xffff0000, v28
	s_waitcnt lgkmcnt(0)
;     ...
;             for (int i = 0; i < 8; ++i) { const int row = i * 4 + (lane2 >> 4); u32x4 v = *(const u32x4*)(stg + row * 128 + ch * 8);
;                 if (mode == 2) { const u32x4 v0 = *(const u32x4*)(stash + row * 128 + ch * 8); float x0[8], x1[8]; unpack8(v0, x0); unpack8(v, x1); float ss = 0.f;
; #pragma unroll
;                     for (int e = 0; e < 8; ++e) { x0[e] = x0[e] - lam * x1[e]; ss += x0[e] * x0[e]; }
;                     ss += __shfl_xor(ss, 1); ss += __shfl_xor(ss, 2); ss += __shfl_xor(ss, 4); ss += __shfl_xor(ss, 8);
;                     const float rstd = rsqrtf(ss * (1.0f / 128) + EPS);
; #pragma unroll
;                     for (int e = 0; e < 8; ++e) x0[e] = x0[e] * rstd * gg[e];
;                     v = pack8(x0); }
;                 *(u32x4*)(Ow + (size_t)row * LDO + ch * 8) = v; }
	v_and_b32_e32 v7, 0xffff0000, v32
	v_lshlrev_b32_e32 v1, 16, v28
	v_lshlrev_b32_e32 v5, 16, v32
	v_fma_f32 v3, -v128, v7, v3
	v_and_b32_e32 v18, 0xffff0000, v29
	v_lshlrev_b32_e32 v19, 16, v29
	v_and_b32_e32 v28, 0xffff0000, v33
	v_lshlrev_b32_e32 v29, 16, v33
	v_fma_f32 v1, -v128, v5, v1
	v_mul_f32_e32 v5, v3, v3
	v_pk_fma_f32 v[18:19], v[128:129], v[28:29], v[18:19] neg_lo:[1,0,0] neg_hi:[1,0,0]
	v_fmac_f32_e32 v5, v1, v1
	v_pk_mul_f32 v[28:29], v[18:19], v[18:19]
	v_and_b32_e32 v32, 0xffff0000, v34
	v_add_f32_e32 v5, v29, v5
	v_add_f32_e32 v5, v28, v5
	v_and_b32_e32 v28, 0xffff0000, v30
	v_lshlrev_b32_e32 v29, 16, v30
	v_lshlrev_b32_e32 v33, 16, v34
	v_pk_fma_f32 v[28:29], v[128:129], v[32:33], v[28:29] neg_lo:[1,0,0] neg_hi:[1,0,0]
	v_and_b32_e32 v30, 0xffff0000, v31
	v_pk_mul_f32 v[32:33], v[28:29], v[28:29]
	v_lshlrev_b32_e32 v31, 16, v31
	v_add_f32_e32 v5, v33, v5
	v_add_f32_e32 v5, v32, v5
	v_and_b32_e32 v32, 0xffff0000, v35
	v_lshlrev_b32_e32 v33, 16, v35
	v_pk_fma_f32 v[30:31], v[128:129], v[32:33], v[30:31] neg_lo:[1,0,0] neg_hi:[1,0,0]
	s_nop 0
	v_pk_mul_f32 v[32:33], v[30:31], v[30:31]
	s_nop 0
	v_add_f32_e32 v5, v33, v5
	v_add_f32_e32 v5, v32, v5
	ds_bpermute_b32 v7, v220, v5
	v_add_u32_e32 v32, 0x38000, v134
	v_mov_b32_e32 v33, v135
	v_lshl_add_u64 v[32:33], v[16:17], 0, v[32:33]
	global_store_dwordx4 v[32:33], v[24:27], off
	s_waitcnt lgkmcnt(0)
	v_add_f32_e32 v5, v5, v7
	ds_bpermute_b32 v7, v221, v5
	s_waitcnt lgkmcnt(0)
	v_add_f32_e32 v5, v5, v7
	ds_bpermute_b32 v7, v222, v5
	s_waitcnt lgkmcnt(0)
	v_add_f32_e32 v5, v5, v7
	ds_bpermute_b32 v7, v223, v5
	s_waitcnt lgkmcnt(0)
	v_add_f32_e32 v5, v5, v7
	v_fmamk_f32 v5, v5, 0x3c000000, v209
	v_mul_f32_e32 v7, 0x4b800000, v5
	v_cmp_gt_f32_e32 vcc, s50, v5
	s_nop 1
	v_cndmask_b32_e32 v5, v5, v7, vcc
	v_rsq_f32_e32 v5, v5
	s_nop 0
	v_mul_f32_e32 v7, 0x45800000, v5
	v_cndmask_b32_e32 v5, v5, v7, vcc
	v_mul_f32_e32 v1, v1, v5
	v_mul_f32_e32 v1, v0, v1
	v_mul_f32_e32 v3, v3, v5
	v_mul_f32_e32 v3, v2, v3
	v_cvt_pk_bf16_f32 v24, v1, v3
	v_or_b32_e32 v1, 0x1800, v22
	v_mul_f32_e32 v7, v19, v5
	v_mul_f32_e32 v9, v18, v5
	v_mul_f32_e32 v11, v29, v5
	v_mul_f32_e32 v13, v28, v5
	v_mul_f32_e32 v15, v31, v5
	v_mul_f32_e32 v5, v30, v5
	v_add_u32_e32 v3, v21, v1
	v_add_u32_e32 v1, v20, v1
	v_mul_f32_e32 v7, v4, v7
	v_mul_f32_e32 v9, v6, v9
	v_mul_f32_e32 v11, v8, v11
	v_mul_f32_e32 v13, v10, v13
	v_mul_f32_e32 v15, v12, v15
	v_mul_f32_e32 v5, v14, v5
	v_cvt_pk_bf16_f32 v25, v7, v9
	v_cvt_pk_bf16_f32 v26, v11, v13
	v_cvt_pk_bf16_f32 v27, v15, v5
	ds_read_b128 v[28:31], v3
	ds_read_b128 v[32:35], v1
	s_waitcnt lgkmcnt(1)
	v_and_b32_e32 v3, 0xffff0000, v28
	s_waitcnt lgkmcnt(0)
	v_and_b32_e32 v7, 0xffff0000, v32
	v_lshlrev_b32_e32 v1, 16, v28
	v_lshlrev_b32_e32 v5, 16, v32
	v_fma_f32 v3, -v128, v7, v3
	v_and_b32_e32 v18, 0xffff0000, v29
	v_lshlrev_b32_e32 v19, 16, v29
	v_and_b32_e32 v28, 0xffff0000, v33
	v_lshlrev_b32_e32 v29, 16, v33
	v_fma_f32 v1, -v128, v5, v1
	v_mul_f32_e32 v5, v3, v3
	v_pk_fma_f32 v[18:19], v[128:129], v[28:29], v[18:19] neg_lo:[1,0,0] neg_hi:[1,0,0]
	v_fmac_f32_e32 v5, v1, v1
	v_pk_mul_f32 v[28:29], v[18:19], v[18:19]
	v_and_b32_e32 v32, 0xffff0000, v34
	v_add_f32_e32 v5, v29, v5
	v_add_f32_e32 v5, v28, v5
	v_and_b32_e32 v28, 0xffff0000, v30
	v_lshlrev_b32_e32 v29, 16, v30
	v_lshlrev_b32_e32 v33, 16, v34
	v_pk_fma_f32 v[28:29], v[128:129], v[32:33], v[28:29] neg_lo:[1,0,0] neg_hi:[1,0,0]
	v_and_b32_e32 v30, 0xffff0000, v31
	v_pk_mul_f32 v[32:33], v[28:29], v[28:29]
	v_lshlrev_b32_e32 v31, 16, v31
	v_add_f32_e32 v5, v33, v5
	v_add_f32_e32 v5, v32, v5
	v_and_b32_e32 v32, 0xffff0000, v35
	v_lshlrev_b32_e32 v33, 16, v35
	v_pk_fma_f32 v[30:31], v[128:129], v[32:33], v[30:31] neg_lo:[1,0,0] neg_hi:[1,0,0]
	s_nop 0
	v_pk_mul_f32 v[32:33], v[30:31], v[30:31]
	s_nop 0
	v_add_f32_e32 v5, v33, v5
	v_add_f32_e32 v5, v32, v5
	ds_bpermute_b32 v7, v220, v5
	v_add_u32_e32 v32, 0x46000, v134
	v_mov_b32_e32 v33, v135
	v_lshl_add_u64 v[32:33], v[16:17], 0, v[32:33]
	global_store_dwordx4 v[32:33], v[24:27], off
	s_waitcnt lgkmcnt(0)
;     ...
;             for (int i = 0; i < 8; ++i) { const int row = i * 4 + (lane2 >> 4); u32x4 v = *(const u32x4*)(stg + row * 128 + ch * 8);
;                 if (mode == 2) { const u32x4 v0 = *(const u32x4*)(stash + row * 128 + ch * 8); float x0[8], x1[8]; unpack8(v0, x0); unpack8(v, x1); float ss = 0.f;
; #pragma unroll
;                     for (int e = 0; e < 8; ++e) { x0[e] = x0[e] - lam * x1[e]; ss += x0[e] * x0[e]; }
;                     ss += __shfl_xor(ss, 1); ss += __shfl_xor(ss, 2); ss += __shfl_xor(ss, 4); ss += __shfl_xor(ss, 8);
;                     const float rstd = rsqrtf(ss * (1.0f / 128) + EPS);
; #pragma unroll
;                     for (int e = 0; e < 8; ++e) x0[e] = x0[e] * rstd * gg[e];
;                     v = pack8(x0); }
;                 *(u32x4*)(Ow + (size_t)row * LDO + ch * 8) = v; }
;         }
;     }
;     asm volatile("s_waitcnt vmcnt(0)" ::: "memory");
;     __syncthreads();
	v_add_f32_e32 v5, v5, v7
	ds_bpermute_b32 v7, v221, v5
	s_waitcnt lgkmcnt(0)
	v_add_f32_e32 v5, v5, v7
	ds_bpermute_b32 v7, v222, v5
	s_waitcnt lgkmcnt(0)
	v_add_f32_e32 v5, v5, v7
	ds_bpermute_b32 v7, v223, v5
	s_waitcnt lgkmcnt(0)
	v_add_f32_e32 v5, v5, v7
	v_fmamk_f32 v5, v5, 0x3c000000, v209
	v_mul_f32_e32 v7, 0x4b800000, v5
	v_cmp_gt_f32_e32 vcc, s50, v5
	s_nop 1
	v_cndmask_b32_e32 v5, v5, v7, vcc
	v_rsq_f32_e32 v5, v5
	s_nop 0
	v_mul_f32_e32 v7, 0x45800000, v5
	v_cndmask_b32_e32 v5, v5, v7, vcc
	v_mul_f32_e32 v1, v1, v5
	v_mul_f32_e32 v1, v0, v1
	v_mul_f32_e32 v3, v3, v5
	v_mul_f32_e32 v3, v2, v3
	v_cvt_pk_bf16_f32 v24, v1, v3
	v_or_b32_e32 v1, 0x1c00, v22
	v_mul_f32_e32 v7, v19, v5
	v_mul_f32_e32 v9, v18, v5
	v_mul_f32_e32 v11, v29, v5
	v_mul_f32_e32 v13, v28, v5
	v_mul_f32_e32 v15, v31, v5
	v_mul_f32_e32 v5, v30, v5
	v_add_u32_e32 v3, v21, v1
	v_add_u32_e32 v1, v20, v1
	v_mul_f32_e32 v7, v4, v7
	v_mul_f32_e32 v9, v6, v9
	v_mul_f32_e32 v11, v8, v11
	v_mul_f32_e32 v13, v10, v13
	v_mul_f32_e32 v15, v12, v15
	v_mul_f32_e32 v5, v14, v5
	v_cvt_pk_bf16_f32 v25, v7, v9
	v_cvt_pk_bf16_f32 v26, v11, v13
	v_cvt_pk_bf16_f32 v27, v15, v5
	ds_read_b128 v[28:31], v3
	ds_read_b128 v[18:21], v1
	s_waitcnt lgkmcnt(1)
	v_and_b32_e32 v3, 0xffff0000, v28
	s_waitcnt lgkmcnt(0)
	v_and_b32_e32 v7, 0xffff0000, v18
	v_lshlrev_b32_e32 v1, 16, v28
	v_lshlrev_b32_e32 v5, 16, v18
	v_fma_f32 v3, -v128, v7, v3
	v_and_b32_e32 v22, 0xffff0000, v29
	v_lshlrev_b32_e32 v23, 16, v29
	v_and_b32_e32 v18, 0xffff0000, v19
	v_lshlrev_b32_e32 v19, 16, v19
	v_fma_f32 v1, -v128, v5, v1
	v_mul_f32_e32 v5, v3, v3
	v_pk_fma_f32 v[18:19], v[128:129], v[18:19], v[22:23] neg_lo:[1,0,0] neg_hi:[1,0,0]
	v_fmac_f32_e32 v5, v1, v1
	v_pk_mul_f32 v[22:23], v[18:19], v[18:19]
	v_and_b32_e32 v28, 0xffff0000, v20
	v_add_f32_e32 v5, v23, v5
	v_add_f32_e32 v5, v22, v5
	v_and_b32_e32 v22, 0xffff0000, v30
	v_lshlrev_b32_e32 v23, 16, v30
	v_lshlrev_b32_e32 v29, 16, v20
	v_pk_fma_f32 v[22:23], v[128:129], v[28:29], v[22:23] neg_lo:[1,0,0] neg_hi:[1,0,0]
	v_and_b32_e32 v20, 0xffff0000, v21
	v_pk_mul_f32 v[28:29], v[22:23], v[22:23]
	v_lshlrev_b32_e32 v21, 16, v21
	v_add_f32_e32 v5, v29, v5
	v_add_f32_e32 v5, v28, v5
	v_and_b32_e32 v28, 0xffff0000, v31
	v_lshlrev_b32_e32 v29, 16, v31
	v_pk_fma_f32 v[20:21], v[128:129], v[20:21], v[28:29] neg_lo:[1,0,0] neg_hi:[1,0,0]
	s_nop 0
	v_pk_mul_f32 v[28:29], v[20:21], v[20:21]
	s_nop 0
	v_add_f32_e32 v5, v29, v5
	v_add_f32_e32 v5, v28, v5
	ds_bpermute_b32 v7, v220, v5
	v_add_u32_e32 v28, 0x54000, v134
	v_mov_b32_e32 v29, v135
	v_lshl_add_u64 v[28:29], v[16:17], 0, v[28:29]
	v_add_u32_e32 v134, 0x62000, v134
	s_waitcnt lgkmcnt(0)
	v_add_f32_e32 v5, v5, v7
	ds_bpermute_b32 v7, v221, v5
	global_store_dwordx4 v[28:29], v[24:27], off
	s_waitcnt lgkmcnt(0)
	v_add_f32_e32 v5, v5, v7
	ds_bpermute_b32 v7, v222, v5
	s_waitcnt lgkmcnt(0)
	v_add_f32_e32 v5, v5, v7
	ds_bpermute_b32 v7, v223, v5
	s_waitcnt lgkmcnt(0)
	v_add_f32_e32 v5, v5, v7
	v_fmamk_f32 v5, v5, 0x3c000000, v209
	v_mul_f32_e32 v7, 0x4b800000, v5
	v_cmp_gt_f32_e32 vcc, s50, v5
	s_nop 1
	v_cndmask_b32_e32 v5, v5, v7, vcc
	v_rsq_f32_e32 v5, v5
	s_nop 0
	v_mul_f32_e32 v7, 0x45800000, v5
	v_cndmask_b32_e32 v5, v5, v7, vcc
	v_mul_f32_e32 v1, v1, v5
	v_mul_f32_e32 v0, v0, v1
	v_mul_f32_e32 v1, v3, v5
	v_mul_f32_e32 v1, v2, v1
	v_mul_f32_e32 v2, v19, v5
	v_mul_f32_e32 v3, v18, v5
	v_mul_f32_e32 v2, v4, v2
	v_mul_f32_e32 v3, v6, v3
	v_mul_f32_e32 v4, v23, v5
	v_mul_f32_e32 v6, v22, v5
	v_mul_f32_e32 v7, v21, v5
	v_mul_f32_e32 v5, v20, v5
	v_mul_f32_e32 v4, v8, v4
	v_mul_f32_e32 v5, v14, v5
	v_mul_f32_e32 v6, v10, v6
	v_mul_f32_e32 v7, v12, v7
	v_cvt_pk_bf16_f32 v0, v0, v1
	v_cvt_pk_bf16_f32 v1, v2, v3
	v_cvt_pk_bf16_f32 v2, v4, v6
	v_cvt_pk_bf16_f32 v3, v7, v5
	v_lshl_add_u64 v[4:5], v[16:17], 0, v[134:135]
	global_store_dwordx4 v[4:5], v[0:3], off
	s_nop 0
	s_barrier
	s_cbranch_scc1 .LBB0_570
